# diff-attn loop: the 16 end-of-half-step exps moved into the last PV MFMA gaps (after the p1 scale / after each staging write)
# speedup vs baseline: 1.0049x; 1.0049x over previous
; __device__ __forceinline__ void partialSM(f32x16& p0, f32x16& p1, float& m_reg, float& mn, float& alpha) {
;     float pmax = p0[0]; for (int r = 1; r < 16; ++r) pmax = fmaxf(pmax, p0[r]); for (int r = 0; r < 16; ++r) pmax = fmaxf(pmax, p1[r]);
;     { auto rr = __builtin_amdgcn_permlane32_swap(__float_as_uint(pmax), __float_as_uint(pmax), false, false);
;       pmax = fmaxf(__uint_as_float(rr[0]), __uint_as_float(rr[1])); }
;     constexpr float C2 = 1.4426950408889634f * SCALE;
;     if (__builtin_expect(__all((pmax - m_reg) * SCALE <= THR), 1)) { mn = m_reg; alpha = 1.f; }
;     else { mn = fmaxf(m_reg, pmax); alpha = __builtin_amdgcn_exp2f((m_reg - mn) * C2); m_reg = mn; }
;     const float mnL = -mn * C2;
;     for (int r = 0; r < 16; ++r) p0[r] = fmaf(p0[r], C2, mnL); for (int r = 0; r < 16; ++r) p1[r] = fmaf(p1[r], C2, mnL);
;     for (int r = 0; r < 16; ++r) p0[r] = __builtin_amdgcn_exp2f(p0[r]);
; }
; template <int VB, bool SK>
; __device__ __forceinline__ void pv_tile(f32x16* o, int vb0, bf16x8 pa0, bf16x8 pa1, bf16x8 pa2, bf16x8 pa3, bool act) {
;     if (SK && !act) return;
;     ...
;     PV_D0(0); PV_D0(1); PV_D0(2); PV_D0(3);
;     ...
; }
.Lh1_nomask:
	v_max_f32_e32 v240, v86, v87
	v_max3_f32 v240, v240, v88, v89
	v_max3_f32 v240, v240, v90, v91
	v_max3_f32 v240, v240, v92, v93
	v_max3_f32 v240, v240, v94, v95
	s_waitcnt lgkmcnt(12)
	v_mfma_f32_32x32x16_bf16 v[34:49], v[102:105], v[114:117], v[34:49]
	ds_read_b64_tr_b16 v[244:245], v202 offset:0x3200
	ds_read_b64_tr_b16 v[246:247], v202 offset:0x3a00
	v_max3_f32 v240, v240, v96, v97
	v_max3_f32 v240, v240, v98, v99
	v_max3_f32 v240, v240, v100, v101
	v_max3_f32 v240, v240, v70, v71
	v_max3_f32 v240, v240, v72, v73
	s_waitcnt lgkmcnt(12)
	v_mfma_f32_32x32x16_bf16 v[34:49], v[66:69], v[118:121], v[34:49]
	ds_read_b64_tr_b16 v[114:115], v202 offset:0x400
	ds_read_b64_tr_b16 v[116:117], v202 offset:0xc00
	v_max3_f32 v240, v240, v74, v75
	v_max3_f32 v240, v240, v76, v77
	v_max3_f32 v240, v240, v78, v79
	v_max3_f32 v240, v240, v80, v81
	v_max3_f32 v240, v240, v82, v83
	s_waitcnt lgkmcnt(12)
	v_mfma_f32_32x32x16_bf16 v[34:49], v[106:109], v[122:125], v[34:49]
	ds_read_b64_tr_b16 v[118:119], v202 offset:0x1400
	ds_read_b64_tr_b16 v[120:121], v202 offset:0x1c00
	v_max3_f32 v240, v240, v84, v85
	v_mov_b32_e32 v241, v240
	s_nop 1
	v_permlane32_swap_b32_e32 v240, v241
	v_max_f32_e32 v240, v240, v241
	s_waitcnt lgkmcnt(12)
	v_mfma_f32_32x32x16_bf16 v[34:49], v[110:113], v[126:129], v[34:49]
	ds_read_b64_tr_b16 v[122:123], v202 offset:0x2400
	ds_read_b64_tr_b16 v[124:125], v202 offset:0x2c00
	v_sub_f32_e32 v241, v240, v252
	v_mul_f32_e32 v241, 0x3db504f3, v241
	v_cmp_ge_f32_e32 vcc, s86, v241
	s_cmp_eq_u64 vcc, exec
	s_cselect_b64 s[4:5], -1, 0
	v_mov_b32_e32 v225, 1.0
	s_waitcnt lgkmcnt(12)
	v_mfma_f32_32x32x16_bf16 v[50:65], v[102:105], v[182:185], v[50:65]
	ds_read_b64_tr_b16 v[126:127], v202 offset:0x3400
	ds_read_b64_tr_b16 v[128:129], v202 offset:0x3c00
	s_cbranch_scc0 .Lh1_rare
.Lh1_back:
	v_fmamk_f32 v228, v86, 0x3e0293ee, v253
	v_fmamk_f32 v229, v87, 0x3e0293ee, v253
	v_fmamk_f32 v230, v88, 0x3e0293ee, v253
	v_fmamk_f32 v231, v89, 0x3e0293ee, v253
	s_waitcnt lgkmcnt(12)
	v_mfma_f32_32x32x16_bf16 v[50:65], v[66:69], v[186:189], v[50:65]
	ds_read_b64_tr_b16 v[182:183], v202 offset:0x600
	ds_read_b64_tr_b16 v[184:185], v202 offset:0xe00
	v_fmamk_f32 v232, v90, 0x3e0293ee, v253
	v_fmamk_f32 v233, v91, 0x3e0293ee, v253
	v_fmamk_f32 v234, v92, 0x3e0293ee, v253
	v_fmamk_f32 v235, v93, 0x3e0293ee, v253
	s_waitcnt lgkmcnt(12)
	v_mfma_f32_32x32x16_bf16 v[50:65], v[106:109], v[190:193], v[50:65]
	ds_read_b64_tr_b16 v[186:187], v202 offset:0x1600
	ds_read_b64_tr_b16 v[188:189], v202 offset:0x1e00
	v_fmamk_f32 v236, v94, 0x3e0293ee, v253
	v_fmamk_f32 v237, v95, 0x3e0293ee, v253
	v_fmamk_f32 v238, v96, 0x3e0293ee, v253
	v_fmamk_f32 v239, v97, 0x3e0293ee, v253
	s_waitcnt lgkmcnt(12)
	v_mfma_f32_32x32x16_bf16 v[50:65], v[110:113], v[244:247], v[50:65]
	ds_read_b64_tr_b16 v[190:191], v202 offset:0x2600
	ds_read_b64_tr_b16 v[192:193], v202 offset:0x2e00
	v_fmamk_f32 v86, v70, 0x3e0293ee, v253
	v_fmamk_f32 v95, v71, 0x3e0293ee, v253
	v_fmamk_f32 v96, v72, 0x3e0293ee, v253
	v_fmamk_f32 v97, v73, 0x3e0293ee, v253
	s_waitcnt lgkmcnt(12)
	v_mfma_f32_32x32x16_bf16 v[18:33], v[102:105], v[114:117], v[18:33]
	ds_read_b64_tr_b16 v[244:245], v202 offset:0x3600
	ds_read_b64_tr_b16 v[246:247], v202 offset:0x3e00
	v_fmamk_f32 v179, v74, 0x3e0293ee, v253
	v_fmamk_f32 v87, v75, 0x3e0293ee, v253
	v_fmamk_f32 v88, v76, 0x3e0293ee, v253
	v_fmamk_f32 v89, v77, 0x3e0293ee, v253
	s_waitcnt lgkmcnt(12)
	v_mfma_f32_32x32x16_bf16 v[18:33], v[66:69], v[118:121], v[18:33]
	v_fmamk_f32 v90, v78, 0x3e0293ee, v253
	v_fmamk_f32 v91, v79, 0x3e0293ee, v253
	v_fmamk_f32 v92, v80, 0x3e0293ee, v253
	v_fmamk_f32 v93, v81, 0x3e0293ee, v253
	s_waitcnt lgkmcnt(10)
	v_mfma_f32_32x32x16_bf16 v[18:33], v[106:109], v[122:125], v[18:33]
	v_fmamk_f32 v98, v98, 0x3e0293ee, v253
	v_fmamk_f32 v99, v99, 0x3e0293ee, v253
	v_fmamk_f32 v100, v100, 0x3e0293ee, v253
	v_fmamk_f32 v101, v101, 0x3e0293ee, v253
	s_waitcnt lgkmcnt(8)
	v_mfma_f32_32x32x16_bf16 v[18:33], v[110:113], v[126:129], v[18:33]
	v_exp_f32_e32 v70, v232
	v_exp_f32_e32 v71, v233
	v_exp_f32_e32 v72, v234
	v_exp_f32_e32 v73, v235
	s_waitcnt lgkmcnt(0)
	s_barrier
	s_waitcnt vmcnt(0)
	v_mfma_f32_32x32x16_bf16 v[2:17], v[102:105], v[182:185], v[2:17]
	ds_write_b128 v209, v[162:165]
	v_exp_f32_e32 v74, v236
	v_exp_f32_e32 v75, v237
	v_exp_f32_e32 v76, v238
	v_exp_f32_e32 v77, v239
	v_mfma_f32_32x32x16_bf16 v[2:17], v[66:69], v[186:189], v[2:17]
	ds_write_b128 v210, v[166:169]
	v_exp_f32_e32 v78, v98
	v_exp_f32_e32 v79, v99
	v_exp_f32_e32 v80, v100
	v_exp_f32_e32 v81, v101
	v_mfma_f32_32x32x16_bf16 v[2:17], v[106:109], v[190:193], v[2:17]
	ds_write_b128 v217, v[170:173] offset:32768
	v_fmamk_f32 v94, v82, 0x3e0293ee, v253
	v_fmamk_f32 v180, v83, 0x3e0293ee, v253
	v_fmamk_f32 v181, v84, 0x3e0293ee, v253
	v_fmamk_f32 v178, v85, 0x3e0293ee, v253
	v_mfma_f32_32x32x16_bf16 v[2:17], v[110:113], v[244:247], v[2:17]
	ds_write_b128 v217, v[174:177] offset:40960
	s_and_b64 vcc, exec, s[4:5]
	s_cbranch_vccnz .Lh1_noresc
	s_and_saveexec_b64 s[52:53], s[0:1]
	ds_write_b32 v219, v225 offset:128
	s_or_b64 exec, exec, s[52:53]
	s_waitcnt lgkmcnt(0)
	ds_read_b128 v[102:105], v218 offset:224
	ds_read_b128 v[106:109], v218 offset:192
	ds_read_b128 v[110:113], v218 offset:160
	ds_read_b128 v[114:117], v218 offset:128
	s_waitcnt lgkmcnt(3)
	v_pk_mul_f32 v[48:49], v[48:49], v[104:105]
	s_waitcnt lgkmcnt(2)
	v_pk_mul_f32 v[44:45], v[44:45], v[108:109]
	s_waitcnt lgkmcnt(1)
	v_pk_mul_f32 v[40:41], v[40:41], v[112:113]
	s_waitcnt lgkmcnt(0)
	v_pk_mul_f32 v[36:37], v[36:37], v[116:117]
	v_pk_mul_f32 v[46:47], v[46:47], v[102:103]
	v_pk_mul_f32 v[42:43], v[42:43], v[106:107]
	v_pk_mul_f32 v[38:39], v[38:39], v[110:111]
	v_pk_mul_f32 v[34:35], v[34:35], v[114:115]
	v_pk_mul_f32 v[64:65], v[64:65], v[104:105]
	v_pk_mul_f32 v[60:61], v[60:61], v[108:109]
	v_pk_mul_f32 v[56:57], v[56:57], v[112:113]
	v_pk_mul_f32 v[52:53], v[52:53], v[116:117]
	v_pk_mul_f32 v[62:63], v[62:63], v[102:103]
	v_pk_mul_f32 v[58:59], v[58:59], v[106:107]
	v_pk_mul_f32 v[54:55], v[54:55], v[110:111]
	v_pk_mul_f32 v[50:51], v[50:51], v[114:115]
	v_pk_mul_f32 v[32:33], v[32:33], v[104:105]
	v_pk_mul_f32 v[28:29], v[28:29], v[108:109]
	v_pk_mul_f32 v[24:25], v[24:25], v[112:113]
	v_pk_mul_f32 v[20:21], v[20:21], v[116:117]
	v_pk_mul_f32 v[30:31], v[30:31], v[102:103]
	v_pk_mul_f32 v[26:27], v[26:27], v[106:107]
	v_pk_mul_f32 v[22:23], v[22:23], v[110:111]
	v_pk_mul_f32 v[18:19], v[18:19], v[114:115]
	v_pk_mul_f32 v[16:17], v[16:17], v[104:105]
	v_pk_mul_f32 v[12:13], v[12:13], v[108:109]
	v_pk_mul_f32 v[8:9], v[8:9], v[112:113]
	v_pk_mul_f32 v[4:5], v[4:5], v[116:117]
	v_pk_mul_f32 v[14:15], v[14:15], v[102:103]
	v_pk_mul_f32 v[10:11], v[10:11], v[106:107]
	v_pk_mul_f32 v[6:7], v[6:7], v[110:111]
	v_pk_mul_f32 v[2:3], v[2:3], v[114:115]
; __device__ __forceinline__ void finishSM(f32x16& p0, f32x16& p1, float alpha, float& l_reg, bf16x8& pa0, bf16x8& pa1, bf16x8& pa2, bf16x8& pa3) {
;     for (int r = 0; r < 16; ++r) p1[r] = __builtin_amdgcn_exp2f(p1[r]);
;     float ps = 0; for (int r = 0; r < 16; ++r) ps += p0[r]; for (int r = 0; r < 16; ++r) ps += p1[r];
;     { auto rr = __builtin_amdgcn_permlane32_swap(__float_as_uint(ps), __float_as_uint(ps), false, false);
;       ps = __uint_as_float(rr[0]) + __uint_as_float(rr[1]); }
;     l_reg = l_reg * alpha + ps;
;     ...
;     PK4(p0, 0, pa0); PK4(p0, 8, pa1); PK4(p1, 0, pa2); PK4(p1, 8, pa3);
;     ...
; }
; template <int KB, bool SK>
; __device__ __forceinline__ void qkt(f32x16& p0, f32x16& p1, const char* K_lds, int r32, int hi, const bf16x8* qr, bool act) {
;     if (SK && !act) { const float NEG = -__builtin_inff();
; #pragma unroll
;         for (int r = 0; r < 16; ++r) { p0[r] = NEG; p1[r] = NEG; } return; }
;     p0 = f32x16{}; p1 = f32x16{};
;     const char* kb[4];
; #pragma unroll
;     for (int dd = 0; dd < 4; ++dd) kb[dd] = K_lds + KB * SHM_K + KSWZ(r32, (dd * 16 + hi * 8) * 2);
; #pragma unroll
;     for (int d0 = 0; d0 < 8; ++d0) { const char* a = kb[d0 & 3] + (d0 >> 2) * 128;
;         bf16x8 b0 = *reinterpret_cast<const bf16x8*>(a);
;         bf16x8 b1 = *reinterpret_cast<const bf16x8*>(a + 32 * 256);
;         const bf16x8 qf = qr[d0];
;         p0 = __builtin_amdgcn_mfma_f32_32x32x16_bf16(b0, qf, p0, 0, 0, 0);
;         p1 = __builtin_amdgcn_mfma_f32_32x32x16_bf16(b1, qf, p1, 0, 0, 0); }
; }
.Lh1_noresc:
	v_exp_f32_e32 v66, v228
	v_exp_f32_e32 v67, v229
	v_exp_f32_e32 v68, v230
	v_exp_f32_e32 v69, v231
	s_waitcnt lgkmcnt(0)
	s_barrier
	ds_read_b128 v[162:165], v211 offset:32768
	ds_read_b128 v[166:169], v211 offset:40960
	ds_read_b128 v[170:173], v212 offset:32768
	ds_read_b128 v[174:177], v212 offset:40960
	ds_read_b128 v[230:233], v213 offset:32768
	ds_read_b128 v[234:237], v213 offset:40960
	ds_read_b128 v[238:241], v214 offset:32768
	ds_read_b128 v[242:245], v214 offset:40960
	v_exp_f32_e32 v82, v86
	v_exp_f32_e32 v83, v95
	v_exp_f32_e32 v84, v96
	v_exp_f32_e32 v85, v97
	v_exp_f32_e32 v86, v179
	v_exp_f32_e32 v87, v87
	s_waitcnt lgkmcnt(7)
	v_mfma_f32_32x32x16_bf16 v[114:129], v[162:165], v[158:161], 0
	ds_read_b128 v[162:165], v211 offset:32896
	v_exp_f32_e32 v88, v88
	v_exp_f32_e32 v89, v89
	v_exp_f32_e32 v90, v90
	v_exp_f32_e32 v91, v91
	v_exp_f32_e32 v92, v92
	s_waitcnt lgkmcnt(7)
	v_mfma_f32_32x32x16_bf16 v[98:113], v[166:169], v[158:161], 0
	ds_read_b128 v[166:169], v211 offset:41088
	v_exp_f32_e32 v93, v93
	v_exp_f32_e32 v94, v94
	v_exp_f32_e32 v95, v180
	v_exp_f32_e32 v96, v181
	v_exp_f32_e32 v97, v178
	s_waitcnt lgkmcnt(7)
	v_mfma_f32_32x32x16_bf16 v[114:129], v[170:173], v[154:157], v[114:129]
	ds_read_b128 v[170:173], v212 offset:32896
	v_add_f32_e32 v178, 0, v66
	v_add_f32_e32 v178, v67, v178
	v_add_f32_e32 v178, v68, v178
	v_add_f32_e32 v178, v69, v178
	v_add_f32_e32 v178, v70, v178
	s_waitcnt lgkmcnt(7)
	v_mfma_f32_32x32x16_bf16 v[98:113], v[174:177], v[154:157], v[98:113]
	ds_read_b128 v[174:177], v212 offset:41088
	v_add_f32_e32 v178, v71, v178
	v_add_f32_e32 v178, v72, v178
	v_add_f32_e32 v178, v73, v178
	v_add_f32_e32 v178, v74, v178
	v_add_f32_e32 v178, v75, v178
	s_waitcnt lgkmcnt(7)
	v_mfma_f32_32x32x16_bf16 v[114:129], v[230:233], v[150:153], v[114:129]
	ds_read_b128 v[230:233], v213 offset:32896
	v_add_f32_e32 v178, v76, v178
	v_add_f32_e32 v178, v77, v178
	v_add_f32_e32 v178, v78, v178
	v_add_f32_e32 v178, v79, v178
	s_waitcnt lgkmcnt(7)
	v_mfma_f32_32x32x16_bf16 v[98:113], v[234:237], v[150:153], v[98:113]
	ds_read_b128 v[234:237], v213 offset:41088
	v_add_f32_e32 v178, v80, v178
	v_add_f32_e32 v178, v81, v178
	v_add_f32_e32 v178, v82, v178
	v_add_f32_e32 v178, v83, v178
	s_waitcnt lgkmcnt(7)
	v_mfma_f32_32x32x16_bf16 v[114:129], v[238:241], v[134:137], v[114:129]
	ds_read_b128 v[238:241], v214 offset:32896
	v_add_f32_e32 v178, v84, v178
	v_add_f32_e32 v178, v85, v178
	v_add_f32_e32 v178, v86, v178
	v_add_f32_e32 v178, v87, v178
	s_waitcnt lgkmcnt(7)
	v_mfma_f32_32x32x16_bf16 v[98:113], v[242:245], v[134:137], v[98:113]
	ds_read_b128 v[242:245], v214 offset:41088
	v_add_f32_e32 v178, v88, v178
	v_add_f32_e32 v178, v89, v178
	v_add_f32_e32 v178, v90, v178
	v_add_f32_e32 v178, v91, v178
	s_waitcnt lgkmcnt(7)
	v_mfma_f32_32x32x16_bf16 v[114:129], v[162:165], v[138:141], v[114:129]
	v_add_f32_e32 v178, v92, v178
	v_add_f32_e32 v178, v93, v178
	v_add_f32_e32 v178, v94, v178
	v_add_f32_e32 v178, v95, v178
	s_waitcnt lgkmcnt(6)
	v_mfma_f32_32x32x16_bf16 v[98:113], v[166:169], v[138:141], v[98:113]
	v_add_f32_e32 v178, v96, v178
	v_add_f32_e32 v228, v97, v178
	v_mov_b32_e32 v229, v228
	s_nop 1
	v_permlane32_swap_b32_e32 v228, v229
	s_waitcnt lgkmcnt(5)
	v_mfma_f32_32x32x16_bf16 v[114:129], v[170:173], v[142:145], v[114:129]
	v_cvt_pk_bf16_f32 v178, v66, v67
	v_cvt_pk_bf16_f32 v179, v68, v69
	v_cvt_pk_bf16_f32 v180, v70, v71
	v_cvt_pk_bf16_f32 v181, v72, v73
	s_waitcnt lgkmcnt(4)
	v_mfma_f32_32x32x16_bf16 v[98:113], v[174:177], v[142:145], v[98:113]
	v_cvt_pk_bf16_f32 v182, v74, v75
	v_cvt_pk_bf16_f32 v183, v76, v77
	v_cvt_pk_bf16_f32 v184, v78, v79
	v_cvt_pk_bf16_f32 v185, v80, v81
	s_waitcnt lgkmcnt(3)
	v_mfma_f32_32x32x16_bf16 v[114:129], v[230:233], v[146:149], v[114:129]
	v_cvt_pk_bf16_f32 v186, v82, v83
	v_cvt_pk_bf16_f32 v187, v84, v85
	v_cvt_pk_bf16_f32 v188, v86, v87
	v_cvt_pk_bf16_f32 v189, v88, v89
	s_waitcnt lgkmcnt(2)
	v_mfma_f32_32x32x16_bf16 v[98:113], v[234:237], v[146:149], v[98:113]
	v_cvt_pk_bf16_f32 v190, v90, v91
	v_cvt_pk_bf16_f32 v191, v92, v93
	v_cvt_pk_bf16_f32 v192, v94, v95
	v_cvt_pk_bf16_f32 v193, v96, v97
	s_waitcnt lgkmcnt(1)
	v_mfma_f32_32x32x16_bf16 v[114:129], v[238:241], v[130:133], v[114:129]
	s_nop 1
	v_permlane32_swap_b32_e32 v178, v180
	v_permlane32_swap_b32_e32 v179, v181
	v_permlane32_swap_b32_e32 v182, v184
	v_permlane32_swap_b32_e32 v183, v185
	s_waitcnt lgkmcnt(0)
	v_mfma_f32_32x32x16_bf16 v[98:113], v[242:245], v[130:133], v[98:113]
	v_permlane32_swap_b32_e32 v186, v188
	v_permlane32_swap_b32_e32 v187, v189
	v_permlane32_swap_b32_e32 v190, v192
	v_permlane32_swap_b32_e32 v191, v193
	s_add_i32 s4, s25, 1
	s_cmp_le_u32 s4, s24
	s_cselect_b64 s[76:77], -1, 0
	s_cmp_gt_u32 s4, s24
	s_cbranch_scc1 .LBB0_1137
	v_add_u32_e32 v84, 0x4000, v255
	v_add_u32_e32 v85, 0x6000, v255
	global_load_dwordx4 v[162:165], v84, s[42:43]
	global_load_dwordx4 v[166:169], v85, s[42:43]
	global_load_dwordx4 v[170:173], v84, s[22:23]
	global_load_dwordx4 v[174:177], v85, s[22:23]

; template <class TIn, class TOut>
; __device__ __forceinline__ void causal_swa_block(const BlockRef<TIn, TOut>& cur, const BlockRef<TIn, TOut>& nxt, int skv, int W, char* lds, Seam<TIn>& S) {
;     ...
;     for (int t = 1; t + 1 < NT; t += 2) {
;         HALF_STEP(pB0, pB1, mnB, alB, pA0, pA1, alA, t, 1, 0, 0);
;         HALF_STEP(pA0, pA1, mnA, alA, pB0, pB1, alB, t + 1, 0, 1, 1);
;     }
.Lh2_back:
	v_fmamk_f32 v68, v114, 0x3e0293ee, v253
	v_fmamk_f32 v69, v115, 0x3e0293ee, v253
	s_waitcnt lgkmcnt(12)
	v_mfma_f32_32x32x16_bf16 v[50:65], v[182:185], v[90:93], v[50:65]
	ds_read_b64_tr_b16 v[86:87], v202 offset:0x4600
	ds_read_b64_tr_b16 v[88:89], v202 offset:0x4e00
	v_fmamk_f32 v70, v116, 0x3e0293ee, v253
	v_fmamk_f32 v71, v117, 0x3e0293ee, v253
	v_fmamk_f32 v79, v118, 0x3e0293ee, v253
	v_fmamk_f32 v80, v119, 0x3e0293ee, v253
	s_waitcnt lgkmcnt(12)
	v_mfma_f32_32x32x16_bf16 v[50:65], v[186:189], v[94:97], v[50:65]
	ds_read_b64_tr_b16 v[90:91], v202 offset:0x5600
	ds_read_b64_tr_b16 v[92:93], v202 offset:0x5e00
	v_fmamk_f32 v72, v120, 0x3e0293ee, v253
	v_fmamk_f32 v73, v121, 0x3e0293ee, v253
	v_fmamk_f32 v81, v122, 0x3e0293ee, v253
	v_fmamk_f32 v82, v123, 0x3e0293ee, v253
	s_waitcnt lgkmcnt(12)
	v_mfma_f32_32x32x16_bf16 v[50:65], v[190:193], v[246:249], v[50:65]
	ds_read_b64_tr_b16 v[94:95], v202 offset:0x6600
	ds_read_b64_tr_b16 v[96:97], v202 offset:0x6e00
	v_fmamk_f32 v74, v124, 0x3e0293ee, v253
	v_fmamk_f32 v75, v125, 0x3e0293ee, v253
	v_fmamk_f32 v76, v126, 0x3e0293ee, v253
	v_fmamk_f32 v77, v127, 0x3e0293ee, v253
	s_waitcnt lgkmcnt(12)
	v_mfma_f32_32x32x16_bf16 v[18:33], v[178:181], v[230:233], v[18:33]
	ds_read_b64_tr_b16 v[246:247], v202 offset:0x7600
	ds_read_b64_tr_b16 v[248:249], v202 offset:0x7e00
	v_fmamk_f32 v83, v128, 0x3e0293ee, v253
	v_fmamk_f32 v78, v129, 0x3e0293ee, v253
	v_fmamk_f32 v126, v98, 0x3e0293ee, v253
	v_fmamk_f32 v127, v99, 0x3e0293ee, v253
	s_waitcnt lgkmcnt(12)
	v_mfma_f32_32x32x16_bf16 v[18:33], v[182:185], v[234:237], v[18:33]
	v_fmamk_f32 v124, v100, 0x3e0293ee, v253
	v_fmamk_f32 v125, v101, 0x3e0293ee, v253
	v_fmamk_f32 v120, v102, 0x3e0293ee, v253
	s_waitcnt lgkmcnt(10)
	v_mfma_f32_32x32x16_bf16 v[18:33], v[186:189], v[238:241], v[18:33]
	v_fmamk_f32 v121, v103, 0x3e0293ee, v253
	v_fmamk_f32 v116, v104, 0x3e0293ee, v253
	v_fmamk_f32 v117, v105, 0x3e0293ee, v253
	s_waitcnt lgkmcnt(8)
	v_mfma_f32_32x32x16_bf16 v[18:33], v[190:193], v[242:245], v[18:33]
	v_fmamk_f32 v114, v106, 0x3e0293ee, v253
	v_fmamk_f32 v115, v107, 0x3e0293ee, v253
	v_fmamk_f32 v128, v108, 0x3e0293ee, v253
	s_waitcnt lgkmcnt(0)
	s_andn2_b64 vcc, exec, s[76:77]
	s_barrier
	s_cbranch_vccnz .Lh2_pvt_nowrite
	s_waitcnt vmcnt(0)
	v_mfma_f32_32x32x16_bf16 v[2:17], v[178:181], v[86:89], v[2:17]
	ds_write_b128 v209, v[162:165] offset:16384
	v_fmamk_f32 v129, v109, 0x3e0293ee, v253
	v_fmamk_f32 v122, v110, 0x3e0293ee, v253
	v_fmamk_f32 v123, v111, 0x3e0293ee, v253
	v_mfma_f32_32x32x16_bf16 v[2:17], v[182:185], v[90:93], v[2:17]
	ds_write_b128 v210, v[166:169] offset:16384
	v_exp_f32_e32 v162, v81
	v_exp_f32_e32 v163, v82
	v_exp_f32_e32 v164, v74
	v_exp_f32_e32 v165, v76
	v_fmamk_f32 v118, v112, 0x3e0293ee, v253
	v_fmamk_f32 v119, v113, 0x3e0293ee, v253
	v_add_f32_e32 v98, v223, v224
	v_mfma_f32_32x32x16_bf16 v[2:17], v[186:189], v[94:97], v[2:17]
	ds_write_b128 v217, v[170:173] offset:49152
	v_exp_f32_e32 v166, v75
	v_exp_f32_e32 v167, v77
	v_exp_f32_e32 v168, v83
	v_exp_f32_e32 v169, v78
	v_fmac_f32_e32 v98, v197, v221
	v_add_f32_e32 v221, v228, v229
	v_fmac_f32_e32 v221, v98, v225
	v_mfma_f32_32x32x16_bf16 v[2:17], v[190:193], v[246:249], v[2:17]
	ds_write_b128 v217, v[174:177] offset:57344
	v_exp_f32_e32 v170, v68
	v_exp_f32_e32 v171, v69
	v_exp_f32_e32 v172, v70
	v_exp_f32_e32 v173, v71
	s_branch .Lh2_pvt_join
.Lh2_pvt_nowrite:
	v_mfma_f32_32x32x16_bf16 v[2:17], v[178:181], v[86:89], v[2:17]
	v_fmamk_f32 v129, v109, 0x3e0293ee, v253
	v_fmamk_f32 v122, v110, 0x3e0293ee, v253
	v_fmamk_f32 v123, v111, 0x3e0293ee, v253
	v_mfma_f32_32x32x16_bf16 v[2:17], v[182:185], v[90:93], v[2:17]
	v_exp_f32_e32 v162, v81
	v_exp_f32_e32 v163, v82
	v_exp_f32_e32 v164, v74
	v_exp_f32_e32 v165, v76
	v_fmamk_f32 v118, v112, 0x3e0293ee, v253
	v_fmamk_f32 v119, v113, 0x3e0293ee, v253
	v_add_f32_e32 v98, v223, v224
	v_mfma_f32_32x32x16_bf16 v[2:17], v[186:189], v[94:97], v[2:17]
	v_exp_f32_e32 v166, v75
	v_exp_f32_e32 v167, v77
	v_exp_f32_e32 v168, v83
	v_exp_f32_e32 v169, v78
	v_fmac_f32_e32 v98, v197, v221
	v_add_f32_e32 v221, v228, v229
	v_fmac_f32_e32 v221, v98, v225
	v_mfma_f32_32x32x16_bf16 v[2:17], v[190:193], v[246:249], v[2:17]
	v_exp_f32_e32 v170, v68
	v_exp_f32_e32 v171, v69
	v_exp_f32_e32 v172, v70
	v_exp_f32_e32 v173, v71
.Lh2_pvt_join:
.Lh2_nowrite:
	v_add_u32_e32 v194, 0x4000, v194
	v_add_u32_e32 v222, 0xffffff80, v222
	v_add_u32_e32 v255, 0x8000, v255
	s_addk_i32 s26, 0x80
	s_add_i32 s25, s25, 2
	s_and_b64 vcc, exec, s[4:5]
	s_cbranch_vccnz .Lh2_noresc
	s_and_saveexec_b64 s[52:53], s[0:1]
	ds_write_b32 v219, v254 offset:128
	s_or_b64 exec, exec, s[52:53]
	s_waitcnt lgkmcnt(0)
	ds_read_b128 v[86:89], v218 offset:224
	ds_read_b128 v[90:93], v218 offset:192
	ds_read_b128 v[94:97], v218 offset:160
	ds_read_b128 v[180:183], v218 offset:128
	s_waitcnt lgkmcnt(3)
	v_pk_mul_f32 v[48:49], v[48:49], v[88:89]
	s_waitcnt lgkmcnt(2)
	v_pk_mul_f32 v[44:45], v[44:45], v[92:93]
	s_waitcnt lgkmcnt(1)
	v_pk_mul_f32 v[40:41], v[40:41], v[96:97]
	s_waitcnt lgkmcnt(0)
	v_pk_mul_f32 v[36:37], v[36:37], v[182:183]
	v_pk_mul_f32 v[46:47], v[46:47], v[86:87]
	v_pk_mul_f32 v[42:43], v[42:43], v[90:91]
	v_pk_mul_f32 v[38:39], v[38:39], v[94:95]
	v_pk_mul_f32 v[34:35], v[34:35], v[180:181]
	v_pk_mul_f32 v[64:65], v[64:65], v[88:89]
	v_pk_mul_f32 v[60:61], v[60:61], v[92:93]
	v_pk_mul_f32 v[56:57], v[56:57], v[96:97]
	v_pk_mul_f32 v[52:53], v[52:53], v[182:183]
	v_pk_mul_f32 v[62:63], v[62:63], v[86:87]
	v_pk_mul_f32 v[58:59], v[58:59], v[90:91]
	v_pk_mul_f32 v[54:55], v[54:55], v[94:95]
	v_pk_mul_f32 v[50:51], v[50:51], v[180:181]
	v_pk_mul_f32 v[32:33], v[32:33], v[88:89]
	v_pk_mul_f32 v[28:29], v[28:29], v[92:93]
	v_pk_mul_f32 v[24:25], v[24:25], v[96:97]
	v_pk_mul_f32 v[20:21], v[20:21], v[182:183]
	v_pk_mul_f32 v[30:31], v[30:31], v[86:87]
	v_pk_mul_f32 v[26:27], v[26:27], v[90:91]
	v_pk_mul_f32 v[22:23], v[22:23], v[94:95]
	v_pk_mul_f32 v[18:19], v[18:19], v[180:181]
	v_pk_mul_f32 v[16:17], v[16:17], v[88:89]
	v_pk_mul_f32 v[12:13], v[12:13], v[92:93]
	v_pk_mul_f32 v[8:9], v[8:9], v[96:97]
	v_pk_mul_f32 v[4:5], v[4:5], v[182:183]
	v_pk_mul_f32 v[14:15], v[14:15], v[86:87]
	v_pk_mul_f32 v[10:11], v[10:11], v[90:91]
	v_pk_mul_f32 v[6:7], v[6:7], v[94:95]
	v_pk_mul_f32 v[2:3], v[2:3], v[180:181]
.Lh2_noresc:
	v_exp_f32_e32 v174, v79
	v_exp_f32_e32 v175, v72
	v_exp_f32_e32 v176, v80
	v_exp_f32_e32 v177, v73
	s_cmp_gt_u32 s25, s24
	s_waitcnt lgkmcnt(0)
	s_barrier
	s_cbranch_scc1 .Lattn_exit
	v_mov_b32_e32 v197, v254
	s_branch .LBB0_1129
